# K-loop: loop-invariant LDS fragment addresses computed once per tile (4 v_add removed per iteration, SP1 reads issue first)
# baseline (speedup 1.0000x reference)
; #define PG8_STAGE(bufoff, gbase, voff) do { _Pragma("unroll") for (int _i = 0; _i < 2; ++_i) \
;         __builtin_amdgcn_global_load_lds((const unsigned*)((const char*)(gbase) + (voff)[_i]), (PG8_LAS unsigned*)(lds + (bufoff) + ldsw + _i * 8192), 16, 0, 0); } while (0)
; #define PG8_LDA(dst, b, h) do { _Pragma("unroll") for (int m = 0; m < 4; ++m) _Pragma("unroll") for (int k = 0; k < 2; ++k) dst[m][k] = *(const PG8_LAS bf16x8*)(lds + PG8_SA(b, h) + aoff + m * 2048 + k * 1024); } while (0)
; #define PG8_LDB(dst, b, h) do { _Pragma("unroll") for (int n = 0; n < 2; ++n) _Pragma("unroll") for (int k = 0; k < 2; ++k) dst[n][k] = *(const PG8_LAS bf16x8*)(lds + PG8_SB(b, h) + boff + n * 2048 + k * 1024); } while (0)
; #define PG8_MMA(ai, bj, At, Bt) do { __builtin_amdgcn_s_setprio(1); _Pragma("unroll") for (int m = 0; m < 4; ++m) _Pragma("unroll") for (int n = 0; n < 2; ++n) _Pragma("unroll") for (int k = 0; k < 2; ++k) \
;         acc[ai][bj][m][n] = __builtin_amdgcn_mfma_f32_16x16x32_bf16(Bt[n][k], At[m][k], acc[ai][bj][m][n], 0, 0, 0); __builtin_amdgcn_s_setprio(0); } while (0)
; #define PG8_WAIT_V(n) asm volatile("s_waitcnt vmcnt(" #n ")" ::: "memory")
; #define PG8_WAIT_L(n) asm volatile("s_waitcnt lgkmcnt(" #n ")" ::: "memory")
; template <class Epi, class Sched, bool ALIGN_EPI = false, bool SP2 = false>
; __device__ __forceinline__ void gemm_phase(PG8_LAS unsigned char* lds, const Gemm g, const Sched& S, const Epi& E) {
;     ...
;             const bool last = (t == nt - 2);
;             const char* a1 = cA + (size_t)(t + 1) * kstep;
;             const char* a2 = last ? nA : cA + (size_t)(t + 2) * kstep; const char* b2 = last ? nB : cB + (size_t)(t + 2) * kstep;
;             const char* a3 = a2 + kstep; const char* b3 = b2 + kstep;
;             if (last && has_next) S.a_ready(nxt);
;             if constexpr (SP2) {
;             PG8_LDB(B0, 0, 0); PG8_LDB(B1, 0, 1); PG8_SCHED; PG8_LDA(At, 0, 0); PG8_STAGE(PG8_SA(1, 1), a1 + hstep, voffA);
;             PG8_WAIT_V(8); PG8_WAIT_L(0); PG8_BAR; PG8_MMA(0, 0, At, B0); PG8_MMA(0, 1, At, B1); PG8_BAR; PG8_SCHED;
;     ...
; #pragma unroll
;         for (int a = 0; a < 2; ++a)
; #pragma unroll
;             for (int b = 0; b < 2; ++b)
; #pragma unroll
;                 for (int m = 0; m < 4; ++m)
; #pragma unroll
;                     for (int n = 0; n < 2; ++n) acc[a][b][m][n] = (f32x4){0.f, 0.f, 0.f, 0.f};
.Lpf_skip:
	v_add_u32_e32 v242, 0x10000, v228
	v_add_u32_e32 v243, 0x14000, v228
	v_add_u32_e32 v244, 0x18000, v228
	v_add_u32_e32 v245, 0x1c000, v228
	v_mov_b64_e32 v[2:3], 0
	v_mov_b64_e32 v[4:5], 0
	v_mov_b64_e32 v[6:7], 0
	v_mov_b64_e32 v[8:9], 0
	v_mov_b64_e32 v[10:11], 0
	v_mov_b64_e32 v[12:13], 0
	v_mov_b64_e32 v[14:15], 0
	v_mov_b64_e32 v[16:17], 0
	v_mov_b64_e32 v[18:19], 0
	v_mov_b64_e32 v[20:21], 0
	v_mov_b64_e32 v[22:23], 0
	v_mov_b64_e32 v[24:25], 0
	v_mov_b64_e32 v[26:27], 0
	v_mov_b64_e32 v[28:29], 0
	v_mov_b64_e32 v[30:31], 0
	v_mov_b64_e32 v[32:33], 0
	v_mov_b64_e32 v[34:35], 0
	v_mov_b64_e32 v[36:37], 0
	v_mov_b64_e32 v[38:39], 0
	v_mov_b64_e32 v[40:41], 0
	v_mov_b64_e32 v[42:43], 0
	v_mov_b64_e32 v[44:45], 0
	v_mov_b64_e32 v[46:47], 0
	v_mov_b64_e32 v[48:49], 0
	v_mov_b64_e32 v[50:51], 0
	v_mov_b64_e32 v[52:53], 0
	v_mov_b64_e32 v[54:55], 0
	v_mov_b64_e32 v[56:57], 0
	v_mov_b64_e32 v[58:59], 0
	v_mov_b64_e32 v[60:61], 0
	v_mov_b64_e32 v[62:63], 0
	v_mov_b64_e32 v[64:65], 0
	v_mov_b64_e32 v[66:67], 0
	v_mov_b64_e32 v[68:69], 0
	v_mov_b64_e32 v[70:71], 0
	v_mov_b64_e32 v[72:73], 0
	v_mov_b64_e32 v[74:75], 0
	v_mov_b64_e32 v[76:77], 0
	v_mov_b64_e32 v[78:79], 0
	v_mov_b64_e32 v[80:81], 0
	v_mov_b64_e32 v[82:83], 0
	v_mov_b64_e32 v[84:85], 0
	v_mov_b64_e32 v[86:87], 0
	v_mov_b64_e32 v[88:89], 0
	v_mov_b64_e32 v[90:91], 0
	v_mov_b64_e32 v[92:93], 0
	v_mov_b64_e32 v[94:95], 0
	v_mov_b64_e32 v[96:97], 0
	v_mov_b64_e32 v[98:99], 0
	v_mov_b64_e32 v[100:101], 0
	v_mov_b64_e32 v[102:103], 0
	v_mov_b64_e32 v[104:105], 0
	v_mov_b64_e32 v[106:107], 0
	v_mov_b64_e32 v[108:109], 0
	v_mov_b64_e32 v[110:111], 0
	v_mov_b64_e32 v[112:113], 0
	v_mov_b64_e32 v[114:115], 0
	v_mov_b64_e32 v[116:117], 0
	v_mov_b64_e32 v[118:119], 0
	v_mov_b64_e32 v[120:121], 0
	v_mov_b64_e32 v[122:123], 0
	v_mov_b64_e32 v[124:125], 0
	v_mov_b64_e32 v[126:127], 0
	v_mov_b64_e32 v[128:129], 0
.LBB0_441:
	s_add_i32 s66, 0, 0x10000
	s_add_i32 s67, 0, 0x14000
	ds_read_b128 v[130:133], v242
	ds_read_b128 v[134:137], v242 offset:1024
	ds_read_b128 v[138:141], v242 offset:2048
	ds_read_b128 v[142:145], v242 offset:3072
	ds_read_b128 v[146:149], v243
	ds_read_b128 v[150:153], v243 offset:1024
	ds_read_b128 v[154:157], v243 offset:2048
	ds_read_b128 v[158:161], v243 offset:3072
	v_lshl_add_u64 v[206:207], s[42:43], 0, v[190:191]
	s_add_i32 m0, s93, 0xc000
	ds_read_b128 v[162:165], v230
	ds_read_b128 v[166:169], v230 offset:1024
	ds_read_b128 v[170:173], v230 offset:2048
	ds_read_b128 v[174:177], v230 offset:3072
	ds_read_b128 v[178:181], v230 offset:4096
	ds_read_b128 v[194:197], v230 offset:5120
	ds_read_b128 v[198:201], v230 offset:6144
	ds_read_b128 v[202:205], v230 offset:7168
	s_add_i32 s61, s44, 2
	s_add_u32 s64, s42, 0x80
	s_addc_u32 s45, s43, 0
	s_cmp_eq_u32 s99, s44
	s_cselect_b32 s45, s29, s45
	s_cselect_b32 s44, s28, s64
	s_cselect_b32 s65, s21, s60
	s_cselect_b32 s64, s20, s17
	global_load_lds_dwordx4 v[206:207], off
	s_add_i32 m0, s93, 0xe000
	v_lshl_add_u64 v[206:207], s[42:43], 0, v[192:193]
	global_load_lds_dwordx4 v[206:207], off
	s_setprio 1
	s_waitcnt vmcnt(8) lgkmcnt(0)
	s_barrier
	v_mfma_f32_16x16x32_bf16 v[126:129], v[130:133], v[162:165], v[126:129]
	v_mfma_f32_16x16x32_bf16 v[122:125], v[138:141], v[162:165], v[122:125]
	v_mfma_f32_16x16x32_bf16 v[110:113], v[130:133], v[170:173], v[110:113]
	v_mfma_f32_16x16x32_bf16 v[102:105], v[138:141], v[170:173], v[102:105]
	v_mfma_f32_16x16x32_bf16 v[94:97], v[130:133], v[178:181], v[94:97]
	v_mfma_f32_16x16x32_bf16 v[86:89], v[138:141], v[178:181], v[86:89]
	v_mfma_f32_16x16x32_bf16 v[78:81], v[130:133], v[198:201], v[78:81]
	v_mfma_f32_16x16x32_bf16 v[70:73], v[138:141], v[198:201], v[70:73]
	v_mfma_f32_16x16x32_bf16 v[126:129], v[134:137], v[166:169], v[126:129]
	v_mfma_f32_16x16x32_bf16 v[122:125], v[142:145], v[166:169], v[122:125]
	v_mfma_f32_16x16x32_bf16 v[110:113], v[134:137], v[174:177], v[110:113]
	v_mfma_f32_16x16x32_bf16 v[102:105], v[142:145], v[174:177], v[102:105]
	v_mfma_f32_16x16x32_bf16 v[94:97], v[134:137], v[194:197], v[94:97]
	v_mfma_f32_16x16x32_bf16 v[86:89], v[142:145], v[194:197], v[86:89]
	v_mfma_f32_16x16x32_bf16 v[78:81], v[134:137], v[202:205], v[78:81]
	v_mfma_f32_16x16x32_bf16 v[70:73], v[142:145], v[202:205], v[70:73]
	v_mfma_f32_16x16x32_bf16 v[118:121], v[146:149], v[162:165], v[118:121]
	v_mfma_f32_16x16x32_bf16 v[114:117], v[154:157], v[162:165], v[114:117]
	v_mfma_f32_16x16x32_bf16 v[106:109], v[146:149], v[170:173], v[106:109]
	v_mfma_f32_16x16x32_bf16 v[98:101], v[154:157], v[170:173], v[98:101]
	v_mfma_f32_16x16x32_bf16 v[90:93], v[146:149], v[178:181], v[90:93]
	v_mfma_f32_16x16x32_bf16 v[82:85], v[154:157], v[178:181], v[82:85]
	v_mfma_f32_16x16x32_bf16 v[74:77], v[146:149], v[198:201], v[74:77]
	v_mfma_f32_16x16x32_bf16 v[66:69], v[154:157], v[198:201], v[66:69]
	v_mfma_f32_16x16x32_bf16 v[118:121], v[150:153], v[166:169], v[118:121]
	v_mfma_f32_16x16x32_bf16 v[114:117], v[158:161], v[166:169], v[114:117]
	v_mfma_f32_16x16x32_bf16 v[106:109], v[150:153], v[174:177], v[106:109]
	v_mfma_f32_16x16x32_bf16 v[98:101], v[158:161], v[174:177], v[98:101]
	v_mfma_f32_16x16x32_bf16 v[90:93], v[150:153], v[194:197], v[90:93]
	v_mfma_f32_16x16x32_bf16 v[82:85], v[158:161], v[194:197], v[82:85]
	v_mfma_f32_16x16x32_bf16 v[74:77], v[150:153], v[202:205], v[74:77]
	v_mfma_f32_16x16x32_bf16 v[66:69], v[158:161], v[202:205], v[66:69]
	s_barrier
; #define PG8_STAGE(bufoff, gbase, voff) do { _Pragma("unroll") for (int _i = 0; _i < 2; ++_i) \
;         __builtin_amdgcn_global_load_lds((const unsigned*)((const char*)(gbase) + (voff)[_i]), (PG8_LAS unsigned*)(lds + (bufoff) + ldsw + _i * 8192), 16, 0, 0); } while (0)
; #define PG8_LDA(dst, b, h) do { _Pragma("unroll") for (int m = 0; m < 4; ++m) _Pragma("unroll") for (int k = 0; k < 2; ++k) dst[m][k] = *(const PG8_LAS bf16x8*)(lds + PG8_SA(b, h) + aoff + m * 2048 + k * 1024); } while (0)
; #define PG8_LDB(dst, b, h) do { _Pragma("unroll") for (int n = 0; n < 2; ++n) _Pragma("unroll") for (int k = 0; k < 2; ++k) dst[n][k] = *(const PG8_LAS bf16x8*)(lds + PG8_SB(b, h) + boff + n * 2048 + k * 1024); } while (0)
; #define PG8_MMA(ai, bj, At, Bt) do { __builtin_amdgcn_s_setprio(1); _Pragma("unroll") for (int m = 0; m < 4; ++m) _Pragma("unroll") for (int n = 0; n < 2; ++n) _Pragma("unroll") for (int k = 0; k < 2; ++k) \
;         acc[ai][bj][m][n] = __builtin_amdgcn_mfma_f32_16x16x32_bf16(Bt[n][k], At[m][k], acc[ai][bj][m][n], 0, 0, 0); __builtin_amdgcn_s_setprio(0); } while (0)
; #define PG8_WAIT_V(n) asm volatile("s_waitcnt vmcnt(" #n ")" ::: "memory")
; #define PG8_WAIT_L(n) asm volatile("s_waitcnt lgkmcnt(" #n ")" ::: "memory")
; #define PG8_BAR __builtin_amdgcn_s_barrier()
; #define PG8_SCHED __builtin_amdgcn_sched_barrier(0)
; template <class Epi, class Sched, bool ALIGN_EPI = false, bool SP2 = false>
; __device__ __forceinline__ void gemm_phase(PG8_LAS unsigned char* lds, const Gemm g, const Sched& S, const Epi& E) {
;     ...
;             PG8_LDA(At, 0, 1); PG8_STAGE(PG8_SB(0, 0), b2, voffB); PG8_STAGE(PG8_SB(0, 1), b2 + hstep, voffB); PG8_STAGE(PG8_SA(0, 0), a2, voffA);
;             PG8_WAIT_V(8); PG8_WAIT_L(0); PG8_BAR; PG8_MMA(1, 0, At, B0); PG8_MMA(1, 1, At, B1); PG8_BAR; PG8_SCHED;
;             PG8_LDB(B0, 1, 0); PG8_LDB(B1, 1, 1); PG8_SCHED; PG8_LDA(At, 1, 0); PG8_STAGE(PG8_SA(0, 1), a2 + hstep, voffA);
	s_setprio 0
	ds_read_b128 v[162:165], v230 offset:16384
	ds_read_b128 v[166:169], v230 offset:17408
	ds_read_b128 v[170:173], v230 offset:18432
	ds_read_b128 v[174:177], v230 offset:19456
	ds_read_b128 v[178:181], v230 offset:20480
	ds_read_b128 v[194:197], v230 offset:21504
	ds_read_b128 v[198:201], v230 offset:22528
	ds_read_b128 v[202:205], v230 offset:23552
	s_add_i32 s66, s66, s92
	s_mov_b32 m0, s66
	v_lshl_add_u64 v[206:207], s[64:65], 0, v[184:185]
	global_load_lds_dwordx4 v[206:207], off
	s_add_i32 m0, s66, 0x2000
	v_lshl_add_u64 v[208:209], s[64:65], 0, v[188:189]
	s_add_u32 s64, s64, s26
	s_addc_u32 s65, s65, 0
	s_add_i32 s66, s67, s92
	global_load_lds_dwordx4 v[208:209], off
	v_lshl_add_u64 v[210:211], s[64:65], 0, v[184:185]
	s_mov_b32 m0, s66
	v_lshl_add_u64 v[232:233], s[64:65], 0, v[188:189]
	global_load_lds_dwordx4 v[210:211], off
	s_add_i32 m0, s66, 0x2000
	v_lshl_add_u64 v[234:235], s[44:45], 0, v[182:183]
	global_load_lds_dwordx4 v[232:233], off
	s_mov_b32 m0, s93
	v_lshl_add_u64 v[236:237], s[44:45], 0, v[186:187]
	global_load_lds_dwordx4 v[234:235], off
	s_mov_b32 m0, s94
	s_nop 0
	global_load_lds_dwordx4 v[236:237], off
	s_setprio 1
	s_waitcnt vmcnt(8) lgkmcnt(0)
	s_barrier
	v_mfma_f32_16x16x32_bf16 v[62:65], v[130:133], v[162:165], v[62:65]
	v_mfma_f32_16x16x32_bf16 v[54:57], v[138:141], v[162:165], v[54:57]
	v_mfma_f32_16x16x32_bf16 v[46:49], v[130:133], v[170:173], v[46:49]
	v_mfma_f32_16x16x32_bf16 v[38:41], v[138:141], v[170:173], v[38:41]
	v_mfma_f32_16x16x32_bf16 v[30:33], v[130:133], v[178:181], v[30:33]
	v_mfma_f32_16x16x32_bf16 v[22:25], v[138:141], v[178:181], v[22:25]
	v_mfma_f32_16x16x32_bf16 v[14:17], v[130:133], v[198:201], v[14:17]
	v_mfma_f32_16x16x32_bf16 v[6:9], v[138:141], v[198:201], v[6:9]
	v_mfma_f32_16x16x32_bf16 v[62:65], v[134:137], v[166:169], v[62:65]
	v_mfma_f32_16x16x32_bf16 v[54:57], v[142:145], v[166:169], v[54:57]
	v_mfma_f32_16x16x32_bf16 v[46:49], v[134:137], v[174:177], v[46:49]
	v_mfma_f32_16x16x32_bf16 v[38:41], v[142:145], v[174:177], v[38:41]
	v_mfma_f32_16x16x32_bf16 v[30:33], v[134:137], v[194:197], v[30:33]
	v_mfma_f32_16x16x32_bf16 v[22:25], v[142:145], v[194:197], v[22:25]
	v_mfma_f32_16x16x32_bf16 v[14:17], v[134:137], v[202:205], v[14:17]
	v_mfma_f32_16x16x32_bf16 v[6:9], v[142:145], v[202:205], v[6:9]
	v_mfma_f32_16x16x32_bf16 v[58:61], v[146:149], v[162:165], v[58:61]
	v_mfma_f32_16x16x32_bf16 v[50:53], v[154:157], v[162:165], v[50:53]
	v_mfma_f32_16x16x32_bf16 v[42:45], v[146:149], v[170:173], v[42:45]
	v_mfma_f32_16x16x32_bf16 v[34:37], v[154:157], v[170:173], v[34:37]
	v_mfma_f32_16x16x32_bf16 v[26:29], v[146:149], v[178:181], v[26:29]
	v_mfma_f32_16x16x32_bf16 v[18:21], v[154:157], v[178:181], v[18:21]
	v_mfma_f32_16x16x32_bf16 v[10:13], v[146:149], v[198:201], v[10:13]
	v_mfma_f32_16x16x32_bf16 v[2:5], v[154:157], v[198:201], v[2:5]
	v_mfma_f32_16x16x32_bf16 v[58:61], v[150:153], v[166:169], v[58:61]
	v_mfma_f32_16x16x32_bf16 v[50:53], v[158:161], v[166:169], v[50:53]
	v_mfma_f32_16x16x32_bf16 v[42:45], v[150:153], v[174:177], v[42:45]
	v_mfma_f32_16x16x32_bf16 v[34:37], v[158:161], v[174:177], v[34:37]
	v_mfma_f32_16x16x32_bf16 v[26:29], v[150:153], v[194:197], v[26:29]
	v_mfma_f32_16x16x32_bf16 v[18:21], v[158:161], v[194:197], v[18:21]
	v_mfma_f32_16x16x32_bf16 v[10:13], v[150:153], v[202:205], v[10:13]
	v_mfma_f32_16x16x32_bf16 v[2:5], v[158:161], v[202:205], v[2:5]
	s_barrier
	s_setprio 0
	ds_read_b128 v[162:165], v230 offset:32768
	ds_read_b128 v[166:169], v230 offset:33792
	ds_read_b128 v[170:173], v230 offset:34816
	ds_read_b128 v[174:177], v230 offset:35840
	ds_read_b128 v[178:181], v230 offset:36864
	ds_read_b128 v[194:197], v230 offset:37888
	ds_read_b128 v[198:201], v230 offset:38912
	ds_read_b128 v[202:205], v230 offset:39936
	s_add_i32 s64, 0, 0x18000
	s_add_i32 s65, 0, 0x1c000
	ds_read_b128 v[130:133], v244
	ds_read_b128 v[134:137], v244 offset:1024
	ds_read_b128 v[138:141], v244 offset:2048
	ds_read_b128 v[142:145], v244 offset:3072
	ds_read_b128 v[146:149], v245
	ds_read_b128 v[150:153], v245 offset:1024
	ds_read_b128 v[154:157], v245 offset:2048
	ds_read_b128 v[158:161], v245 offset:3072
	s_add_u32 s44, s44, s26
	s_addc_u32 s45, s45, 0
	s_mov_b32 m0, s95
	v_lshl_add_u64 v[238:239], s[44:45], 0, v[182:183]
	global_load_lds_dwordx4 v[238:239], off
	s_mov_b32 m0, s96
	v_lshl_add_u64 v[238:239], s[44:45], 0, v[186:187]
	global_load_lds_dwordx4 v[238:239], off
	s_setprio 1
	s_waitcnt vmcnt(8) lgkmcnt(0)
	s_barrier
; #define PG8_STAGE(bufoff, gbase, voff) do { _Pragma("unroll") for (int _i = 0; _i < 2; ++_i) \
;         __builtin_amdgcn_global_load_lds((const unsigned*)((const char*)(gbase) + (voff)[_i]), (PG8_LAS unsigned*)(lds + (bufoff) + ldsw + _i * 8192), 16, 0, 0); } while (0)
; #define PG8_LDA(dst, b, h) do { _Pragma("unroll") for (int m = 0; m < 4; ++m) _Pragma("unroll") for (int k = 0; k < 2; ++k) dst[m][k] = *(const PG8_LAS bf16x8*)(lds + PG8_SA(b, h) + aoff + m * 2048 + k * 1024); } while (0)
; #define PG8_MMA(ai, bj, At, Bt) do { __builtin_amdgcn_s_setprio(1); _Pragma("unroll") for (int m = 0; m < 4; ++m) _Pragma("unroll") for (int n = 0; n < 2; ++n) _Pragma("unroll") for (int k = 0; k < 2; ++k) \
;         acc[ai][bj][m][n] = __builtin_amdgcn_mfma_f32_16x16x32_bf16(Bt[n][k], At[m][k], acc[ai][bj][m][n], 0, 0, 0); __builtin_amdgcn_s_setprio(0); } while (0)
; #define PG8_WAIT_V(n) asm volatile("s_waitcnt vmcnt(" #n ")" ::: "memory")
; #define PG8_WAIT_L(n) asm volatile("s_waitcnt lgkmcnt(" #n ")" ::: "memory")
; #define PG8_BAR __builtin_amdgcn_s_barrier()
; #define PG8_SCHED __builtin_amdgcn_sched_barrier(0)
; template <class Epi, class Sched, bool ALIGN_EPI = false, bool SP2 = false>
; __device__ __forceinline__ void gemm_phase(PG8_LAS unsigned char* lds, const Gemm g, const Sched& S, const Epi& E) {
;     ...
;             PG8_WAIT_V(8); PG8_WAIT_L(0); PG8_BAR; PG8_MMA(0, 0, At, B0); PG8_MMA(0, 1, At, B1); PG8_BAR; PG8_SCHED;
;             PG8_LDA(At, 1, 1); PG8_STAGE(PG8_SB(1, 0), b3, voffB); PG8_STAGE(PG8_SB(1, 1), b3 + hstep, voffB); PG8_STAGE(PG8_SA(1, 0), a3, voffA);
;             PG8_WAIT_V(8); PG8_WAIT_L(0); PG8_BAR; PG8_MMA(1, 0, At, B0); PG8_MMA(1, 1, At, B1); PG8_BAR; PG8_SCHED;
;     ...
;         if constexpr (ALIGN_EPI) { if (wr == 0) PG8_BAR; }
;         if constexpr (!Epi::AFTER_DRAIN) { E(acc, cur, wr, wc, fr, fq); S.done(cur); }
	v_mfma_f32_16x16x32_bf16 v[126:129], v[130:133], v[162:165], v[126:129]
	v_mfma_f32_16x16x32_bf16 v[122:125], v[138:141], v[162:165], v[122:125]
	v_mfma_f32_16x16x32_bf16 v[110:113], v[130:133], v[170:173], v[110:113]
	v_mfma_f32_16x16x32_bf16 v[102:105], v[138:141], v[170:173], v[102:105]
	v_mfma_f32_16x16x32_bf16 v[94:97], v[130:133], v[178:181], v[94:97]
	v_mfma_f32_16x16x32_bf16 v[86:89], v[138:141], v[178:181], v[86:89]
	v_mfma_f32_16x16x32_bf16 v[78:81], v[130:133], v[198:201], v[78:81]
	v_mfma_f32_16x16x32_bf16 v[70:73], v[138:141], v[198:201], v[70:73]
	v_mfma_f32_16x16x32_bf16 v[126:129], v[134:137], v[166:169], v[126:129]
	v_mfma_f32_16x16x32_bf16 v[122:125], v[142:145], v[166:169], v[122:125]
	v_mfma_f32_16x16x32_bf16 v[110:113], v[134:137], v[174:177], v[110:113]
	v_mfma_f32_16x16x32_bf16 v[102:105], v[142:145], v[174:177], v[102:105]
	v_mfma_f32_16x16x32_bf16 v[94:97], v[134:137], v[194:197], v[94:97]
	v_mfma_f32_16x16x32_bf16 v[86:89], v[142:145], v[194:197], v[86:89]
	v_mfma_f32_16x16x32_bf16 v[78:81], v[134:137], v[202:205], v[78:81]
	v_mfma_f32_16x16x32_bf16 v[70:73], v[142:145], v[202:205], v[70:73]
	v_mfma_f32_16x16x32_bf16 v[118:121], v[146:149], v[162:165], v[118:121]
	v_mfma_f32_16x16x32_bf16 v[114:117], v[154:157], v[162:165], v[114:117]
	v_mfma_f32_16x16x32_bf16 v[106:109], v[146:149], v[170:173], v[106:109]
	v_mfma_f32_16x16x32_bf16 v[98:101], v[154:157], v[170:173], v[98:101]
	v_mfma_f32_16x16x32_bf16 v[90:93], v[146:149], v[178:181], v[90:93]
	v_mfma_f32_16x16x32_bf16 v[82:85], v[154:157], v[178:181], v[82:85]
	v_mfma_f32_16x16x32_bf16 v[74:77], v[146:149], v[198:201], v[74:77]
	v_mfma_f32_16x16x32_bf16 v[66:69], v[154:157], v[198:201], v[66:69]
	v_mfma_f32_16x16x32_bf16 v[118:121], v[150:153], v[166:169], v[118:121]
	v_mfma_f32_16x16x32_bf16 v[114:117], v[158:161], v[166:169], v[114:117]
	v_mfma_f32_16x16x32_bf16 v[106:109], v[150:153], v[174:177], v[106:109]
	v_mfma_f32_16x16x32_bf16 v[98:101], v[158:161], v[174:177], v[98:101]
	v_mfma_f32_16x16x32_bf16 v[90:93], v[150:153], v[194:197], v[90:93]
	v_mfma_f32_16x16x32_bf16 v[82:85], v[158:161], v[194:197], v[82:85]
	v_mfma_f32_16x16x32_bf16 v[74:77], v[150:153], v[202:205], v[74:77]
	v_mfma_f32_16x16x32_bf16 v[66:69], v[158:161], v[202:205], v[66:69]
	s_barrier
	s_setprio 0
	ds_read_b128 v[162:165], v230 offset:49152
	ds_read_b128 v[166:169], v230 offset:50176
	ds_read_b128 v[170:173], v230 offset:51200
	ds_read_b128 v[174:177], v230 offset:52224
	ds_read_b128 v[178:181], v230 offset:53248
	ds_read_b128 v[194:197], v230 offset:54272
	ds_read_b128 v[198:201], v230 offset:55296
	ds_read_b128 v[202:205], v230 offset:56320
	s_add_i32 s44, s64, s92
	s_mov_b32 m0, s44
	v_lshl_add_u64 v[206:207], v[206:207], 0, s[34:35]
	global_load_lds_dwordx4 v[206:207], off
	v_lshl_add_u64 v[206:207], v[208:209], 0, s[34:35]
	s_add_i32 m0, s44, 0x2000
	s_add_i32 s44, s65, s92
	global_load_lds_dwordx4 v[206:207], off
	s_mov_b32 m0, s44
	v_lshl_add_u64 v[206:207], v[210:211], 0, s[34:35]
	global_load_lds_dwordx4 v[206:207], off
	s_add_i32 m0, s44, 0x2000
	v_lshl_add_u64 v[206:207], v[232:233], 0, s[34:35]
	global_load_lds_dwordx4 v[206:207], off
	s_mov_b32 m0, s97
	v_lshl_add_u64 v[206:207], v[234:235], 0, s[34:35]
	global_load_lds_dwordx4 v[206:207], off
	s_mov_b32 m0, s98
	v_lshl_add_u64 v[206:207], v[236:237], 0, s[34:35]
	global_load_lds_dwordx4 v[206:207], off
	s_add_u32 s42, s42, 0x100
	s_addc_u32 s43, s43, 0
	s_add_u32 s17, s17, 0x100
	s_addc_u32 s60, s60, 0
	s_cmp_ge_u32 s61, s4
	s_mov_b32 s44, s61
	s_setprio 1
	s_waitcnt vmcnt(8) lgkmcnt(0)
	s_barrier
	v_mfma_f32_16x16x32_bf16 v[62:65], v[130:133], v[162:165], v[62:65]
	v_mfma_f32_16x16x32_bf16 v[54:57], v[138:141], v[162:165], v[54:57]
	v_mfma_f32_16x16x32_bf16 v[46:49], v[130:133], v[170:173], v[46:49]
	v_mfma_f32_16x16x32_bf16 v[38:41], v[138:141], v[170:173], v[38:41]
	v_mfma_f32_16x16x32_bf16 v[30:33], v[130:133], v[178:181], v[30:33]
	v_mfma_f32_16x16x32_bf16 v[22:25], v[138:141], v[178:181], v[22:25]
	v_mfma_f32_16x16x32_bf16 v[14:17], v[130:133], v[198:201], v[14:17]
	v_mfma_f32_16x16x32_bf16 v[6:9], v[138:141], v[198:201], v[6:9]
	v_mfma_f32_16x16x32_bf16 v[62:65], v[134:137], v[166:169], v[62:65]
	v_mfma_f32_16x16x32_bf16 v[54:57], v[142:145], v[166:169], v[54:57]
	v_mfma_f32_16x16x32_bf16 v[46:49], v[134:137], v[174:177], v[46:49]
	v_mfma_f32_16x16x32_bf16 v[38:41], v[142:145], v[174:177], v[38:41]
	v_mfma_f32_16x16x32_bf16 v[30:33], v[134:137], v[194:197], v[30:33]
	v_mfma_f32_16x16x32_bf16 v[22:25], v[142:145], v[194:197], v[22:25]
	v_mfma_f32_16x16x32_bf16 v[14:17], v[134:137], v[202:205], v[14:17]
	v_mfma_f32_16x16x32_bf16 v[6:9], v[142:145], v[202:205], v[6:9]
	v_mfma_f32_16x16x32_bf16 v[58:61], v[146:149], v[162:165], v[58:61]
	v_mfma_f32_16x16x32_bf16 v[50:53], v[154:157], v[162:165], v[50:53]
	v_mfma_f32_16x16x32_bf16 v[42:45], v[146:149], v[170:173], v[42:45]
	v_mfma_f32_16x16x32_bf16 v[34:37], v[154:157], v[170:173], v[34:37]
	v_mfma_f32_16x16x32_bf16 v[26:29], v[146:149], v[178:181], v[26:29]
	v_mfma_f32_16x16x32_bf16 v[18:21], v[154:157], v[178:181], v[18:21]
	v_mfma_f32_16x16x32_bf16 v[10:13], v[146:149], v[198:201], v[10:13]
	v_mfma_f32_16x16x32_bf16 v[2:5], v[154:157], v[198:201], v[2:5]
	v_mfma_f32_16x16x32_bf16 v[58:61], v[150:153], v[166:169], v[58:61]
	v_mfma_f32_16x16x32_bf16 v[50:53], v[158:161], v[166:169], v[50:53]
	v_mfma_f32_16x16x32_bf16 v[42:45], v[150:153], v[174:177], v[42:45]
	v_mfma_f32_16x16x32_bf16 v[34:37], v[158:161], v[174:177], v[34:37]
	v_mfma_f32_16x16x32_bf16 v[26:29], v[150:153], v[194:197], v[26:29]
	v_mfma_f32_16x16x32_bf16 v[18:21], v[158:161], v[194:197], v[18:21]
	v_mfma_f32_16x16x32_bf16 v[10:13], v[150:153], v[202:205], v[10:13]
	v_mfma_f32_16x16x32_bf16 v[2:5], v[158:161], v[202:205], v[2:5]
	s_barrier
	s_setprio 0
	s_cbranch_scc0 .LBB0_441
	s_and_b64 vcc, exec, s[36:37]
	s_cbranch_vccz .LBB0_445
	s_barrier
	s_cmp_lt_i32 s0, 2
	s_mov_b64 s[42:43], -1
	s_cbranch_scc0 .LBB0_446
